# in-proj epilogue head: row-statistics lane reductions via v_permlane16/32_swap instead of ds_bpermute round trips
# speedup vs baseline: 1.0465x; 1.0014x over previous
;     __device__ __forceinline__ void operator()(const f32x4 (&acc)[2][2][4][2], const Unit& u, int wr, int wc, int fr, int fq) const {
;         const int row0 = u.pm * BM + wr * 64 + fr;
;         float rsv[2][4];
; #pragma unroll
;         for (int ai = 0; ai < 2; ++ai) {
; #pragma unroll
;             for (int m = 0; m < 4; ++m) {
;                 const int row = row0 + ai * HALF + m * 16;
;                 const f32x4 h0 = *((const f32x4*)(hss + (size_t)row * 16) + fq);
;                 float ss = (h0[0] + h0[1]) + (h0[2] + h0[3]);
;                 ss += __shfl_xor(ss, 16); ss += __shfl_xor(ss, 32);
;                 rsv[ai][m] = 1.0f / sqrtf(ss * (1.0f / 1024.0f) + 1e-6f);
.LBB0_143:
	v_and_b32_e32 v148, 64, v216
	v_xor_b32_e32 v0, 16, v216
	v_add_u32_e32 v148, 64, v148
	v_cmp_lt_i32_e32 vcc, v0, v148
	v_lshl_add_u32 v160, s44, 8, v139
	v_ashrrev_i32_e32 v161, 31, v160
	v_cndmask_b32_e32 v0, v216, v0, vcc
	v_lshlrev_b32_e32 v173, 2, v0
	v_xor_b32_e32 v0, 32, v216
	v_cmp_lt_i32_e32 vcc, v0, v148
	v_lshlrev_b64 v[148:149], 6, v[160:161]
	v_lshl_add_u64 v[148:149], v[142:143], 0, v[148:149]
	v_lshlrev_b64 v[248:249], 6, v[160:161]
	v_lshl_add_u64 v[248:249], v[142:143], 0, v[248:249]
	global_load_dwordx4 v[222:225], v[248:249], off
	v_add_u32_e32 v248, 0x10, v160
	v_ashrrev_i32_e32 v249, 31, v248
	v_lshlrev_b64 v[248:249], 6, v[248:249]
	v_lshl_add_u64 v[248:249], v[142:143], 0, v[248:249]
	global_load_dwordx4 v[226:229], v[248:249], off
	v_add_u32_e32 v248, 0x20, v160
	v_ashrrev_i32_e32 v249, 31, v248
	v_lshlrev_b64 v[248:249], 6, v[248:249]
	v_lshl_add_u64 v[248:249], v[142:143], 0, v[248:249]
	global_load_dwordx4 v[230:233], v[248:249], off
	v_add_u32_e32 v248, 0x30, v160
	v_ashrrev_i32_e32 v249, 31, v248
	v_lshlrev_b64 v[248:249], 6, v[248:249]
	v_lshl_add_u64 v[248:249], v[142:143], 0, v[248:249]
	global_load_dwordx4 v[234:237], v[248:249], off
	v_add_u32_e32 v248, 0x80, v160
	v_ashrrev_i32_e32 v249, 31, v248
	v_lshlrev_b64 v[248:249], 6, v[248:249]
	v_lshl_add_u64 v[248:249], v[142:143], 0, v[248:249]
	global_load_dwordx4 v[238:241], v[248:249], off
	v_add_u32_e32 v248, 0x90, v160
	v_ashrrev_i32_e32 v249, 31, v248
	v_lshlrev_b64 v[248:249], 6, v[248:249]
	v_lshl_add_u64 v[248:249], v[142:143], 0, v[248:249]
	global_load_dwordx4 v[242:245], v[248:249], off
	v_add_u32_e32 v248, 0xa0, v160
	v_ashrrev_i32_e32 v249, 31, v248
	v_lshlrev_b64 v[248:249], 6, v[248:249]
	v_lshl_add_u64 v[248:249], v[142:143], 0, v[248:249]
	global_load_dwordx4 v[180:183], v[248:249], off
	v_add_u32_e32 v248, 0xb0, v160
	v_ashrrev_i32_e32 v249, 31, v248
	v_lshlrev_b64 v[248:249], 6, v[248:249]
	v_lshl_add_u64 v[248:249], v[142:143], 0, v[248:249]
	global_load_dwordx4 v[184:187], v[248:249], off
	s_waitcnt vmcnt(0)
	v_mov_b64_e32 v[148:149], v[222:223]
	v_mov_b64_e32 v[150:151], v[224:225]
	v_cndmask_b32_e32 v0, v216, v0, vcc
	v_lshlrev_b32_e32 v0, 2, v0
	v_or_b32_e32 v164, 16, v160
	v_ashrrev_i32_e32 v165, 31, v164
	v_or_b32_e32 v158, 32, v160
	v_ashrrev_i32_e32 v159, 31, v158
	v_or_b32_e32 v156, 48, v160
	v_ashrrev_i32_e32 v157, 31, v156
	v_add_u32_e32 v154, 0x80, v160
	v_ashrrev_i32_e32 v155, 31, v154
	s_cmp_gt_i32 s43, 15
	s_cselect_b64 s[8:9], -1, 0
	s_waitcnt lgkmcnt(0)
	v_add_f32_e32 v148, v148, v149
	v_add_f32_e32 v149, v150, v151
	v_add_f32_e32 v148, v148, v149
	v_mov_b32_e32 v149, v148
	s_nop 1
	v_permlane16_swap_b32_e32 v148, v149
	s_waitcnt lgkmcnt(0)
	v_add_f32_e32 v148, v148, v149
	v_mov_b32_e32 v149, v148
	s_nop 1
	v_permlane32_swap_b32_e32 v148, v149
	s_waitcnt lgkmcnt(0)
	v_add_f32_e32 v148, v148, v149
	v_fmamk_f32 v148, v148, 0x3a800000, v211
	v_cmp_gt_f32_e32 vcc, s55, v148
	v_mul_f32_e32 v149, 0x4f800000, v148
	s_nop 0
	v_cndmask_b32_e32 v148, v148, v149, vcc
	v_sqrt_f32_e32 v149, v148
	s_nop 0
	v_add_u32_e32 v150, -1, v149
	v_fma_f32 v151, -v150, v149, v148
	v_cmp_ge_f32_e64 s[0:1], 0, v151
	v_add_u32_e32 v151, 1, v149
	s_nop 0
	v_cndmask_b32_e64 v150, v149, v150, s[0:1]
	v_fma_f32 v149, -v151, v149, v148
	v_cmp_lt_f32_e64 s[0:1], 0, v149
	s_nop 1
	v_cndmask_b32_e64 v149, v150, v151, s[0:1]
	v_mul_f32_e32 v150, 0x37800000, v149
	v_cndmask_b32_e32 v149, v149, v150, vcc
	v_cmp_class_f32_e32 vcc, v148, v212
	s_nop 1
	v_cndmask_b32_e32 v148, v149, v148, vcc
	v_div_scale_f32 v149, s[0:1], v148, v148, 1.0
	v_rcp_f32_e32 v150, v149
	s_mov_b64 s[0:1], -1
	v_fma_f32 v151, -v149, v150, 1.0
	v_fmac_f32_e32 v150, v151, v150
	v_div_scale_f32 v151, vcc, 1.0, v148, 1.0
	v_mul_f32_e32 v152, v151, v150
	v_fma_f32 v153, -v149, v152, v151
	v_fmac_f32_e32 v152, v153, v150
	v_fma_f32 v149, -v149, v152, v151
	v_div_fmas_f32 v149, v149, v150, v152
	v_div_fixup_f32 v162, v149, v148, 1.0
	v_lshlrev_b64 v[148:149], 6, v[164:165]
	v_lshl_add_u64 v[148:149], v[142:143], 0, v[148:149]
	v_mov_b64_e32 v[148:149], v[226:227]
	v_mov_b64_e32 v[150:151], v[228:229]
	v_add_u32_e32 v152, 0x90, v160
	v_ashrrev_i32_e32 v153, 31, v152
	s_and_b64 vcc, exec, s[8:9]
	s_waitcnt lgkmcnt(0)
;     __device__ __forceinline__ void operator()(const f32x4 (&acc)[2][2][4][2], const Unit& u, int wr, int wc, int fr, int fq) const {
;     ...
;                 const int row = row0 + ai * HALF + m * 16;
;                 const f32x4 h0 = *((const f32x4*)(hss + (size_t)row * 16) + fq);
;                 float ss = (h0[0] + h0[1]) + (h0[2] + h0[3]);
;                 ss += __shfl_xor(ss, 16); ss += __shfl_xor(ss, 32);
;                 rsv[ai][m] = 1.0f / sqrtf(ss * (1.0f / 1024.0f) + 1e-6f);
;     ...
;                 } else {
;                     const int c0 = wc * 32 + 8 * fq;
;                     if (c0 < 72) {
;                         *(f32x4*)(misc + (size_t)row * 80 + c0) = acc[ai][0][m][0] * rs;
;                         *(f32x4*)(misc + (size_t)row * 80 + c0 + 4) = acc[ai][0][m][1] * rs;
;                     }
	v_add_f32_e32 v148, v148, v149
	v_add_f32_e32 v149, v150, v151
	v_add_f32_e32 v148, v148, v149
	v_mov_b32_e32 v149, v148
	s_nop 1
	v_permlane16_swap_b32_e32 v148, v149
	s_waitcnt lgkmcnt(0)
	v_add_f32_e32 v171, v148, v149
	v_lshlrev_b64 v[148:149], 6, v[158:159]
	v_lshl_add_u64 v[148:149], v[142:143], 0, v[148:149]
	v_mov_b64_e32 v[148:149], v[230:231]
	v_mov_b64_e32 v[150:151], v[232:233]
	v_mov_b32_e32 v172, v171
	s_nop 1
	v_permlane32_swap_b32_e32 v171, v172
	s_waitcnt lgkmcnt(0)
	v_add_f32_e32 v148, v148, v149
	v_add_f32_e32 v149, v150, v151
	v_add_f32_e32 v148, v148, v149
	v_mov_b32_e32 v149, v148
	s_nop 1
	v_permlane16_swap_b32_e32 v148, v149
	s_waitcnt lgkmcnt(0)
	v_add_f32_e32 v169, v148, v149
	v_lshlrev_b64 v[148:149], 6, v[156:157]
	v_lshl_add_u64 v[148:149], v[142:143], 0, v[148:149]
	v_mov_b64_e32 v[148:149], v[234:235]
	v_mov_b64_e32 v[150:151], v[236:237]
	v_mov_b32_e32 v170, v169
	s_nop 1
	v_permlane32_swap_b32_e32 v169, v170
	s_waitcnt lgkmcnt(0)
	v_add_f32_e32 v148, v148, v149
	v_add_f32_e32 v149, v150, v151
	v_add_f32_e32 v148, v148, v149
	v_mov_b32_e32 v149, v148
	s_nop 1
	v_permlane16_swap_b32_e32 v148, v149
	s_waitcnt lgkmcnt(0)
	v_add_f32_e32 v167, v148, v149
	v_lshlrev_b64 v[148:149], 6, v[154:155]
	v_lshl_add_u64 v[148:149], v[142:143], 0, v[148:149]
	v_mov_b64_e32 v[148:149], v[238:239]
	v_mov_b64_e32 v[150:151], v[240:241]
	v_mov_b32_e32 v168, v167
	s_nop 1
	v_permlane32_swap_b32_e32 v167, v168
	s_waitcnt lgkmcnt(0)
	v_add_f32_e32 v148, v148, v149
	v_add_f32_e32 v149, v150, v151
	v_add_f32_e32 v148, v148, v149
	v_mov_b32_e32 v149, v148
	s_nop 1
	v_permlane16_swap_b32_e32 v148, v149
	s_waitcnt lgkmcnt(0)
	v_add_f32_e32 v161, v148, v149
	v_lshlrev_b64 v[148:149], 6, v[152:153]
	v_lshl_add_u64 v[148:149], v[142:143], 0, v[148:149]
	v_mov_b64_e32 v[148:149], v[242:243]
	v_mov_b64_e32 v[150:151], v[244:245]
	v_mov_b32_e32 v165, v161
	s_nop 1
	v_permlane32_swap_b32_e32 v161, v165
	s_waitcnt lgkmcnt(0)
	v_add_f32_e32 v148, v148, v149
	v_add_f32_e32 v149, v150, v151
	v_add_f32_e32 v148, v148, v149
	v_mov_b32_e32 v149, v148
	s_nop 1
	v_permlane16_swap_b32_e32 v148, v149
	v_add_u32_e32 v150, 0xa0, v160
	v_ashrrev_i32_e32 v151, 31, v150
	s_waitcnt lgkmcnt(0)
	v_add_f32_e32 v155, v148, v149
	v_lshlrev_b64 v[148:149], 6, v[150:151]
	v_lshl_add_u64 v[148:149], v[142:143], 0, v[148:149]
	v_mov_b64_e32 v[174:175], v[180:181]
	v_mov_b64_e32 v[176:177], v[182:183]
	v_mov_b32_e32 v157, v155
	s_nop 1
	v_permlane32_swap_b32_e32 v155, v157
	s_waitcnt lgkmcnt(0)
	v_add_f32_e32 v148, v174, v175
	v_add_f32_e32 v149, v176, v177
	v_add_f32_e32 v148, v148, v149
	v_mov_b32_e32 v149, v148
	s_nop 1
	v_permlane16_swap_b32_e32 v148, v149
	s_waitcnt lgkmcnt(0)
	v_add_f32_e32 v151, v148, v149
	v_add_u32_e32 v148, 0xb0, v160
	v_ashrrev_i32_e32 v149, 31, v148
	v_lshlrev_b64 v[174:175], 6, v[148:149]
	v_lshl_add_u64 v[174:175], v[142:143], 0, v[174:175]
	v_mov_b64_e32 v[174:175], v[184:185]
	v_mov_b64_e32 v[176:177], v[186:187]
	v_mov_b32_e32 v153, v151
	s_nop 1
	v_permlane32_swap_b32_e32 v151, v153
	s_waitcnt lgkmcnt(0)
	v_add_f32_e32 v149, v174, v175
	v_add_f32_e32 v159, v176, v177
	v_add_f32_e32 v149, v149, v159
	v_mov_b32_e32 v159, v149
	s_nop 1
	v_permlane16_swap_b32_e32 v149, v159
	s_waitcnt lgkmcnt(0)
	v_add_f32_e32 v149, v149, v159
	v_mov_b32_e32 v159, v149
	s_nop 1
	v_permlane32_swap_b32_e32 v149, v159
	s_cbranch_vccz .LBB0_147
	s_and_saveexec_b64 s[0:1], s[6:7]
	s_cbranch_execz .LBB0_146
	s_movk_i32 s17, 0x140
	v_pk_mul_f32 v[176:177], v[128:129], v[162:163] op_sel_hi:[1,0]
	v_pk_mul_f32 v[174:175], v[126:127], v[162:163] op_sel_hi:[1,0]
	v_mad_i64_i32 v[178:179], s[26:27], v160, s17, v[140:141]
	global_store_dwordx4 v[178:179], v[174:177], off
	s_nop 1
	v_pk_mul_f32 v[176:177], v[124:125], v[162:163] op_sel_hi:[1,0]
	v_pk_mul_f32 v[174:175], v[122:123], v[162:163] op_sel_hi:[1,0]
	global_store_dwordx4 v[178:179], v[174:177], off offset:16

;     __device__ __forceinline__ void operator()(const f32x4 (&acc)[2][2][4][2], const Unit& u, int wr, int wc, int fr, int fq) const {
;         const int row0 = u.pm * BM + wr * 64 + fr;
;         float rsv[2][4];
; #pragma unroll
;         for (int ai = 0; ai < 2; ++ai) {
; #pragma unroll
;             for (int m = 0; m < 4; ++m) {
;                 const int row = row0 + ai * HALF + m * 16;
;                 const f32x4 h0 = *((const f32x4*)(hss + (size_t)row * 16) + fq);
;                 float ss = (h0[0] + h0[1]) + (h0[2] + h0[3]);
;                 ss += __shfl_xor(ss, 16); ss += __shfl_xor(ss, 32);
;                 rsv[ai][m] = 1.0f / sqrtf(ss * (1.0f / 1024.0f) + 1e-6f);
.LBB0_381:
	v_and_b32_e32 v148, 64, v216
	v_xor_b32_e32 v0, 16, v216
	v_add_u32_e32 v148, 64, v148
	v_cmp_lt_i32_e32 vcc, v0, v148
	v_lshl_add_u32 v160, s46, 8, v139
	v_ashrrev_i32_e32 v161, 31, v160
	v_cndmask_b32_e32 v0, v216, v0, vcc
	v_lshlrev_b32_e32 v173, 2, v0
	v_xor_b32_e32 v0, 32, v216
	v_cmp_lt_i32_e32 vcc, v0, v148
	v_lshlrev_b64 v[148:149], 6, v[160:161]
	v_lshl_add_u64 v[148:149], v[142:143], 0, v[148:149]
	v_lshlrev_b64 v[248:249], 6, v[160:161]
	v_lshl_add_u64 v[248:249], v[142:143], 0, v[248:249]
	global_load_dwordx4 v[222:225], v[248:249], off
	v_add_u32_e32 v248, 0x10, v160
	v_ashrrev_i32_e32 v249, 31, v248
	v_lshlrev_b64 v[248:249], 6, v[248:249]
	v_lshl_add_u64 v[248:249], v[142:143], 0, v[248:249]
	global_load_dwordx4 v[226:229], v[248:249], off
	v_add_u32_e32 v248, 0x20, v160
	v_ashrrev_i32_e32 v249, 31, v248
	v_lshlrev_b64 v[248:249], 6, v[248:249]
	v_lshl_add_u64 v[248:249], v[142:143], 0, v[248:249]
	global_load_dwordx4 v[230:233], v[248:249], off
	v_add_u32_e32 v248, 0x30, v160
	v_ashrrev_i32_e32 v249, 31, v248
	v_lshlrev_b64 v[248:249], 6, v[248:249]
	v_lshl_add_u64 v[248:249], v[142:143], 0, v[248:249]
	global_load_dwordx4 v[234:237], v[248:249], off
	v_add_u32_e32 v248, 0x80, v160
	v_ashrrev_i32_e32 v249, 31, v248
	v_lshlrev_b64 v[248:249], 6, v[248:249]
	v_lshl_add_u64 v[248:249], v[142:143], 0, v[248:249]
	global_load_dwordx4 v[238:241], v[248:249], off
	v_add_u32_e32 v248, 0x90, v160
	v_ashrrev_i32_e32 v249, 31, v248
	v_lshlrev_b64 v[248:249], 6, v[248:249]
	v_lshl_add_u64 v[248:249], v[142:143], 0, v[248:249]
	global_load_dwordx4 v[242:245], v[248:249], off
	v_add_u32_e32 v248, 0xa0, v160
	v_ashrrev_i32_e32 v249, 31, v248
	v_lshlrev_b64 v[248:249], 6, v[248:249]
	v_lshl_add_u64 v[248:249], v[142:143], 0, v[248:249]
	global_load_dwordx4 v[180:183], v[248:249], off
	v_add_u32_e32 v248, 0xb0, v160
	v_ashrrev_i32_e32 v249, 31, v248
	v_lshlrev_b64 v[248:249], 6, v[248:249]
	v_lshl_add_u64 v[248:249], v[142:143], 0, v[248:249]
	global_load_dwordx4 v[184:187], v[248:249], off
	s_waitcnt vmcnt(0)
	v_mov_b64_e32 v[148:149], v[222:223]
	v_mov_b64_e32 v[150:151], v[224:225]
	v_cndmask_b32_e32 v0, v216, v0, vcc
	v_lshlrev_b32_e32 v0, 2, v0
	v_or_b32_e32 v164, 16, v160
	v_ashrrev_i32_e32 v165, 31, v164
	v_or_b32_e32 v158, 32, v160
	v_ashrrev_i32_e32 v159, 31, v158
	v_or_b32_e32 v156, 48, v160
	v_ashrrev_i32_e32 v157, 31, v156
	v_add_u32_e32 v154, 0x80, v160
	v_ashrrev_i32_e32 v155, 31, v154
	s_cmp_gt_i32 s45, 15
	s_cselect_b64 s[8:9], -1, 0
	s_waitcnt lgkmcnt(0)
	v_add_f32_e32 v148, v148, v149
	v_add_f32_e32 v149, v150, v151
	v_add_f32_e32 v148, v148, v149
	v_mov_b32_e32 v149, v148
	s_nop 1
	v_permlane16_swap_b32_e32 v148, v149
	s_waitcnt lgkmcnt(0)
	v_add_f32_e32 v148, v148, v149
	v_mov_b32_e32 v149, v148
	s_nop 1
	v_permlane32_swap_b32_e32 v148, v149
	s_waitcnt lgkmcnt(0)
	v_add_f32_e32 v148, v148, v149
	v_fmamk_f32 v148, v148, 0x3a800000, v211
	v_cmp_gt_f32_e32 vcc, s55, v148
	v_mul_f32_e32 v149, 0x4f800000, v148
	s_nop 0
	v_cndmask_b32_e32 v148, v148, v149, vcc
	v_sqrt_f32_e32 v149, v148
	s_nop 0
	v_add_u32_e32 v150, -1, v149
	v_fma_f32 v151, -v150, v149, v148
	v_cmp_ge_f32_e64 s[0:1], 0, v151
	v_add_u32_e32 v151, 1, v149
	s_nop 0
	v_cndmask_b32_e64 v150, v149, v150, s[0:1]
	v_fma_f32 v149, -v151, v149, v148
	v_cmp_lt_f32_e64 s[0:1], 0, v149
	s_nop 1
	v_cndmask_b32_e64 v149, v150, v151, s[0:1]
	v_mul_f32_e32 v150, 0x37800000, v149
	v_cndmask_b32_e32 v149, v149, v150, vcc
	v_cmp_class_f32_e32 vcc, v148, v212
	s_nop 1
	v_cndmask_b32_e32 v148, v149, v148, vcc
	v_div_scale_f32 v149, s[0:1], v148, v148, 1.0
	v_rcp_f32_e32 v150, v149
	s_mov_b64 s[0:1], -1
	v_fma_f32 v151, -v149, v150, 1.0
	v_fmac_f32_e32 v150, v151, v150
	v_div_scale_f32 v151, vcc, 1.0, v148, 1.0
	v_mul_f32_e32 v152, v151, v150
	v_fma_f32 v153, -v149, v152, v151
	v_fmac_f32_e32 v152, v153, v150
	v_fma_f32 v149, -v149, v152, v151
	v_div_fmas_f32 v149, v149, v150, v152
	v_div_fixup_f32 v162, v149, v148, 1.0
	v_lshlrev_b64 v[148:149], 6, v[164:165]
	v_lshl_add_u64 v[148:149], v[142:143], 0, v[148:149]
	v_mov_b64_e32 v[148:149], v[226:227]
	v_mov_b64_e32 v[150:151], v[228:229]
	v_add_u32_e32 v152, 0x90, v160
	v_ashrrev_i32_e32 v153, 31, v152
	s_and_b64 vcc, exec, s[8:9]
	s_waitcnt lgkmcnt(0)
;     __device__ __forceinline__ void operator()(const f32x4 (&acc)[2][2][4][2], const Unit& u, int wr, int wc, int fr, int fq) const {
;     ...
;                 const int row = row0 + ai * HALF + m * 16;
;                 const f32x4 h0 = *((const f32x4*)(hss + (size_t)row * 16) + fq);
;                 float ss = (h0[0] + h0[1]) + (h0[2] + h0[3]);
;                 ss += __shfl_xor(ss, 16); ss += __shfl_xor(ss, 32);
;                 rsv[ai][m] = 1.0f / sqrtf(ss * (1.0f / 1024.0f) + 1e-6f);
;     ...
;                 } else {
;                     const int c0 = wc * 32 + 8 * fq;
;                     if (c0 < 72) {
;                         *(f32x4*)(misc + (size_t)row * 80 + c0) = acc[ai][0][m][0] * rs;
;                         *(f32x4*)(misc + (size_t)row * 80 + c0 + 4) = acc[ai][0][m][1] * rs;
;                     }
	v_add_f32_e32 v148, v148, v149
	v_add_f32_e32 v149, v150, v151
	v_add_f32_e32 v148, v148, v149
	v_mov_b32_e32 v149, v148
	s_nop 1
	v_permlane16_swap_b32_e32 v148, v149
	s_waitcnt lgkmcnt(0)
	v_add_f32_e32 v171, v148, v149
	v_lshlrev_b64 v[148:149], 6, v[158:159]
	v_lshl_add_u64 v[148:149], v[142:143], 0, v[148:149]
	v_mov_b64_e32 v[148:149], v[230:231]
	v_mov_b64_e32 v[150:151], v[232:233]
	v_mov_b32_e32 v172, v171
	s_nop 1
	v_permlane32_swap_b32_e32 v171, v172
	s_waitcnt lgkmcnt(0)
	v_add_f32_e32 v148, v148, v149
	v_add_f32_e32 v149, v150, v151
	v_add_f32_e32 v148, v148, v149
	v_mov_b32_e32 v149, v148
	s_nop 1
	v_permlane16_swap_b32_e32 v148, v149
	s_waitcnt lgkmcnt(0)
	v_add_f32_e32 v169, v148, v149
	v_lshlrev_b64 v[148:149], 6, v[156:157]
	v_lshl_add_u64 v[148:149], v[142:143], 0, v[148:149]
	v_mov_b64_e32 v[148:149], v[234:235]
	v_mov_b64_e32 v[150:151], v[236:237]
	v_mov_b32_e32 v170, v169
	s_nop 1
	v_permlane32_swap_b32_e32 v169, v170
	s_waitcnt lgkmcnt(0)
	v_add_f32_e32 v148, v148, v149
	v_add_f32_e32 v149, v150, v151
	v_add_f32_e32 v148, v148, v149
	v_mov_b32_e32 v149, v148
	s_nop 1
	v_permlane16_swap_b32_e32 v148, v149
	s_waitcnt lgkmcnt(0)
	v_add_f32_e32 v167, v148, v149
	v_lshlrev_b64 v[148:149], 6, v[154:155]
	v_lshl_add_u64 v[148:149], v[142:143], 0, v[148:149]
	v_mov_b64_e32 v[148:149], v[238:239]
	v_mov_b64_e32 v[150:151], v[240:241]
	v_mov_b32_e32 v168, v167
	s_nop 1
	v_permlane32_swap_b32_e32 v167, v168
	s_waitcnt lgkmcnt(0)
	v_add_f32_e32 v148, v148, v149
	v_add_f32_e32 v149, v150, v151
	v_add_f32_e32 v148, v148, v149
	v_mov_b32_e32 v149, v148
	s_nop 1
	v_permlane16_swap_b32_e32 v148, v149
	s_waitcnt lgkmcnt(0)
	v_add_f32_e32 v161, v148, v149
	v_lshlrev_b64 v[148:149], 6, v[152:153]
	v_lshl_add_u64 v[148:149], v[142:143], 0, v[148:149]
	v_mov_b64_e32 v[148:149], v[242:243]
	v_mov_b64_e32 v[150:151], v[244:245]
	v_mov_b32_e32 v165, v161
	s_nop 1
	v_permlane32_swap_b32_e32 v161, v165
	s_waitcnt lgkmcnt(0)
	v_add_f32_e32 v148, v148, v149
	v_add_f32_e32 v149, v150, v151
	v_add_f32_e32 v148, v148, v149
	v_mov_b32_e32 v149, v148
	s_nop 1
	v_permlane16_swap_b32_e32 v148, v149
	v_add_u32_e32 v150, 0xa0, v160
	v_ashrrev_i32_e32 v151, 31, v150
	s_waitcnt lgkmcnt(0)
	v_add_f32_e32 v155, v148, v149
	v_lshlrev_b64 v[148:149], 6, v[150:151]
	v_lshl_add_u64 v[148:149], v[142:143], 0, v[148:149]
	v_mov_b64_e32 v[174:175], v[180:181]
	v_mov_b64_e32 v[176:177], v[182:183]
	v_mov_b32_e32 v157, v155
	s_nop 1
	v_permlane32_swap_b32_e32 v155, v157
	s_waitcnt lgkmcnt(0)
	v_add_f32_e32 v148, v174, v175
	v_add_f32_e32 v149, v176, v177
	v_add_f32_e32 v148, v148, v149
	v_mov_b32_e32 v149, v148
	s_nop 1
	v_permlane16_swap_b32_e32 v148, v149
	s_waitcnt lgkmcnt(0)
	v_add_f32_e32 v151, v148, v149
	v_add_u32_e32 v148, 0xb0, v160
	v_ashrrev_i32_e32 v149, 31, v148
	v_lshlrev_b64 v[174:175], 6, v[148:149]
	v_lshl_add_u64 v[174:175], v[142:143], 0, v[174:175]
	v_mov_b64_e32 v[174:175], v[184:185]
	v_mov_b64_e32 v[176:177], v[186:187]
	v_mov_b32_e32 v153, v151
	s_nop 1
	v_permlane32_swap_b32_e32 v151, v153
	s_waitcnt lgkmcnt(0)
	v_add_f32_e32 v149, v174, v175
	v_add_f32_e32 v159, v176, v177
	v_add_f32_e32 v149, v149, v159
	v_mov_b32_e32 v159, v149
	s_nop 1
	v_permlane16_swap_b32_e32 v149, v159
	s_waitcnt lgkmcnt(0)
	v_add_f32_e32 v149, v149, v159
	v_mov_b32_e32 v159, v149
	s_nop 1
	v_permlane32_swap_b32_e32 v149, v159
	s_cbranch_vccz .LBB0_385
	s_and_saveexec_b64 s[0:1], s[6:7]
	s_cbranch_execz .LBB0_384
	s_movk_i32 s19, 0x140
	v_pk_mul_f32 v[176:177], v[128:129], v[162:163] op_sel_hi:[1,0]
	v_pk_mul_f32 v[174:175], v[126:127], v[162:163] op_sel_hi:[1,0]
	v_mad_i64_i32 v[178:179], s[28:29], v160, s19, v[140:141]
	global_store_dwordx4 v[178:179], v[174:177], off
	s_nop 1
	v_pk_mul_f32 v[176:177], v[124:125], v[162:163] op_sel_hi:[1,0]
	v_pk_mul_f32 v[174:175], v[122:123], v[162:163] op_sel_hi:[1,0]
	global_store_dwordx4 v[178:179], v[174:177], off offset:16
